# GroupNorm pass: once-read inputs also loaded non-temporally (on top of the non-temporal P0 input loads)
# baseline (speedup 1.0000x reference)
; __device__ __forceinline__ f32x4 bf4(v2u u) { return (f32x4){bflo(u.x), bfhi(u.x), bflo(u.y), bfhi(u.y)}; }
; __device__ __forceinline__ v2u pk4(f32x4 v) { v2u o; o.x = pk2(v.x, v.y); o.y = pk2(v.z, v.w); return o; }
; __device__ __forceinline__ void p3_gn_chunk(const Args& a, int ch, int lane) {
;     const int n = lane & 15, rg = lane >> 4, head = ch & 15, c0 = head * 64 + 4 * n; const int t0 = (ch >> 4) * 16 + 4 * rg;
;     const bf16* YR = (const bf16*)(a.ws + WS_YR); const bf16* ZB = (const bf16*)(a.ws + WS_ZB); bf16* Y = (bf16*)(a.ws + WS_XN); const float* RK = (const float*)(a.ws + WS_RK);
;     const f32x4 lw = ld4(a.in[16] + c0), lb = ld4(a.in[17] + c0);
;     f32x4 vimg[4];
; #pragma unroll
;     for (int cb = 0; cb < 4; ++cb) vimg[cb] = bf4(*(const v2u*)(a.ws + WS_VS + (size_t)ch * 2048 + cb * 512 + lane * 8));
; #pragma unroll
;     for (int e = 0; e < 4; ++e) { const int t = t0 + e;
;         f32x4 y = bf4(*(const v2u*)(YR + (size_t)t * 1024 + c0));
;         const f32x4 g = bf4(*(const v2u*)(ZB + (size_t)t * 5120 + 4096 + c0)); const float rk = RK[(size_t)t * 16 + head];
;         const float mean = row16_sum((y.x + y.y) + (y.z + y.w)) * (1.f / 64.f);
;         y = y - mean;
;         const float rstd = __builtin_amdgcn_rsqf(row16_sum((y.x * y.x + y.y * y.y) + (y.z * y.z + y.w * y.w)) * (1.f / 64.f) + GN_EPS);
;         const f32x4 v = {vimg[0][e], vimg[1][e], vimg[2][e], vimg[3][e]};
;         f32x4 o = y * rstd * lw + lb + v * rk;
; #pragma unroll
;         for (int k = 0; k < 4; ++k) o[k] *= g[k] * __builtin_amdgcn_rcpf(1.f + __expf(-g[k]));
;         *(v2u*)(Y + (size_t)t * 2048 + c0) = pk4(o); }
.LBB0_640:
	s_lshl_b32 s100, s8, 11
	v_lshl_add_u64 v[128:129], s[100:101], 0, v[130:131]
	s_and_b32 s4, s8, 15
	s_and_b32 s5, s8, -16
	v_lshl_or_b32 v0, s4, 6, v30
	v_add_u32_e32 v26, s5, v31
	s_lshl_b32 s4, s4, 2
	v_lshlrev_b32_e32 v10, 1, v0
	v_ashrrev_i32_e32 v27, 31, v26
	v_mad_i64_i32 v[28:29], s[10:11], v26, s6, v[12:13]
	s_add_u32 s4, s2, s4
	v_or_b32_e32 v34, 1, v26
	v_or_b32_e32 v36, 2, v26
	v_or_b32_e32 v22, 3, v26
	v_lshl_add_u64 v[38:39], s[72:73], 0, v[10:11]
	v_lshlrev_b64 v[40:41], 11, v[26:27]
	v_lshl_add_u64 v[28:29], v[28:29], 0, v[10:11]
	v_lshlrev_b32_e32 v23, 2, v0
	s_addc_u32 s5, s3, 0
	v_lshlrev_b64 v[42:43], 6, v[26:27]
	v_mad_i64_i32 v[44:45], s[10:11], v34, s6, v[12:13]
	v_mad_i64_i32 v[46:47], s[10:11], v36, s6, v[12:13]
	v_mad_i64_i32 v[48:49], s[10:11], v22, s6, v[12:13]
	v_lshl_add_u64 v[40:41], v[38:39], 0, v[40:41]
	v_add_co_u32_e32 v28, vcc, s7, v28
	global_load_dwordx2 v[14:15], v[8:9], off nt
	global_load_dwordx2 v[16:17], v[8:9], off offset:512 nt
	global_load_dwordx2 v[18:19], v[8:9], off offset:1024 nt
	global_load_dwordx2 v[20:21], v[8:9], off offset:1536 nt
	global_load_dwordx4 v[0:3], v23, s[12:13] nt
	global_load_dwordx4 v[4:7], v23, s[14:15] nt
	v_lshl_add_u64 v[24:25], s[60:61], 0, v[10:11]
	v_addc_co_u32_e32 v29, vcc, 0, v29, vcc
	v_lshl_add_u64 v[42:43], s[4:5], 0, v[42:43]
	v_lshl_add_u64 v[44:45], v[44:45], 0, v[10:11]
	v_lshl_add_u64 v[46:47], v[46:47], 0, v[10:11]
	v_lshl_add_u64 v[48:49], v[48:49], 0, v[10:11]
	global_load_dwordx2 v[120:121], v[128:129], off nt
	global_load_dwordx2 v[122:123], v[128:129], off offset:512 nt
	global_load_dwordx2 v[124:125], v[128:129], off offset:1024 nt
	global_load_dwordx2 v[126:127], v[128:129], off offset:1536 nt
	s_nop 0
	global_load_dwordx2 v[60:61], v[28:29], off nt
	global_load_dword v10, v[42:43], off nt
	v_ashrrev_i32_e32 v35, 31, v34
	v_ashrrev_i32_e32 v37, 31, v36
	v_lshlrev_b64 v[50:51], 11, v[34:35]
	v_lshlrev_b64 v[52:53], 6, v[34:35]
	v_lshlrev_b64 v[54:55], 11, v[36:37]
	v_lshlrev_b64 v[56:57], 6, v[36:37]
	v_add_co_u32_e32 v42, vcc, s7, v44
	v_lshl_add_u64 v[28:29], v[38:39], 0, v[50:51]
	s_nop 0
	v_addc_co_u32_e32 v43, vcc, 0, v45, vcc
	v_lshl_add_u64 v[44:45], s[4:5], 0, v[52:53]
	v_lshl_add_u64 v[50:51], v[38:39], 0, v[54:55]
	v_lshl_add_u64 v[52:53], s[4:5], 0, v[56:57]
	v_lshlrev_b64 v[26:27], 12, v[26:27]
	v_lshl_add_u64 v[26:27], v[24:25], 0, v[26:27]
	v_lshlrev_b64 v[34:35], 12, v[34:35]
	v_lshl_add_u64 v[34:35], v[24:25], 0, v[34:35]
	v_add_co_u32_e32 v46, vcc, s7, v46
	v_ashrrev_i32_e32 v23, 31, v22
	s_nop 0
	v_addc_co_u32_e32 v47, vcc, 0, v47, vcc
	v_lshlrev_b64 v[58:59], 11, v[22:23]
	v_lshl_add_u64 v[38:39], v[38:39], 0, v[58:59]
	v_lshlrev_b64 v[36:37], 12, v[36:37]
	v_lshl_add_u64 v[36:37], v[24:25], 0, v[36:37]
	v_add_co_u32_e32 v48, vcc, s7, v48
	s_add_i32 s8, s8, s42
	s_nop 0
	v_addc_co_u32_e32 v49, vcc, 0, v49, vcc
	v_lshl_add_u64 v[8:9], v[8:9], 0, s[0:1]
	s_cmpk_gt_i32 s8, 0x3fff
	v_lshlrev_b64 v[118:119], 6, v[22:23]
	s_nop 0
	global_load_dwordx2 v[102:103], v[42:43], off nt
	global_load_dword v104, v[44:45], off nt
	v_lshl_add_u64 v[118:119], s[4:5], 0, v[118:119]
	s_nop 0
	global_load_dwordx2 v[108:109], v[46:47], off nt
	global_load_dword v110, v[52:53], off nt
	s_nop 0
	global_load_dwordx2 v[114:115], v[48:49], off nt
	global_load_dword v116, v[118:119], off nt
	s_waitcnt vmcnt(17)
	v_lshlrev_b32_e32 v54, 16, v14
	v_and_b32_e32 v56, 0xffff0000, v14
	s_waitcnt vmcnt(16)
	v_lshlrev_b32_e32 v55, 16, v16
	v_and_b32_e32 v57, 0xffff0000, v16
	s_waitcnt vmcnt(15)
	v_lshlrev_b32_e32 v62, 16, v18
	v_and_b32_e32 v64, 0xffff0000, v18
	s_waitcnt vmcnt(14)
	v_lshlrev_b32_e32 v63, 16, v20
	v_and_b32_e32 v65, 0xffff0000, v20
	v_lshlrev_b32_e32 v58, 16, v15
	v_lshlrev_b32_e32 v59, 16, v17
	s_waitcnt vmcnt(8)
	v_perm_b32 v40, v122, v120, s98
	v_perm_b32 v41, v126, v124, s98
	v_perm_b32 v100, v122, v120, s99
	v_perm_b32 v101, v126, v124, s99
	v_perm_b32 v106, v123, v121, s98
	v_perm_b32 v107, v127, v125, s98
	v_perm_b32 v112, v123, v121, s99
	v_perm_b32 v113, v127, v125, s99
	v_lshlrev_b32_e32 v69, 16, v41
	v_lshlrev_b32_e32 v68, 16, v40
	v_and_b32_e32 v41, 0xffff0000, v41
	v_and_b32_e32 v40, 0xffff0000, v40
	v_pk_add_f32 v[72:73], v[68:69], v[40:41]
	s_waitcnt vmcnt(7)
	v_lshlrev_b32_e32 v70, 16, v60
	v_add_f32_e32 v33, v72, v73
	v_mul_f32_e32 v14, 0xbfb8aa3b, v70
	v_exp_f32_e32 v14, v14
	v_add_f32_dpp v33, v33, v33 quad_perm:[1,0,3,2] row_mask:0xf bank_mask:0xf bound_ctrl:1
	v_and_b32_e32 v71, 0xffff0000, v60
	v_lshlrev_b32_e32 v60, 16, v61
	v_add_f32_dpp v33, v33, v33 quad_perm:[2,3,0,1] row_mask:0xf bank_mask:0xf bound_ctrl:1
	v_add_f32_e32 v14, 1.0, v14
	v_rcp_f32_e32 v72, v14
	v_add_f32_dpp v33, v33, v33 row_half_mirror row_mask:0xf bank_mask:0xf bound_ctrl:1
	v_and_b32_e32 v61, 0xffff0000, v61
	v_mul_f32_e32 v16, 0xbfb8aa3b, v71
	v_add_f32_dpp v33, v33, v33 row_mirror row_mask:0xf bank_mask:0xf bound_ctrl:1
	v_fmac_f32_e32 v40, 0xbc800000, v33
	v_fmac_f32_e32 v41, 0xbc800000, v33
	v_fmac_f32_e32 v69, 0xbc800000, v33
	v_fmac_f32_e32 v68, 0xbc800000, v33
	v_mov_b32_e32 v76, v69
	v_mov_b32_e32 v77, v41
	v_mov_b32_e32 v69, v40
	v_pk_mul_f32 v[40:41], v[76:77], v[76:77]
	v_pk_mul_f32 v[78:79], v[68:69], v[68:69]
	v_mul_f32_e32 v18, 0xbfb8aa3b, v60
	v_pk_mov_b32 v[80:81], v[78:79], v[40:41] op_sel:[1,0]
	v_mov_b32_e32 v79, v41
	v_pk_add_f32 v[40:41], v[80:81], v[78:79]
	v_mul_f32_e32 v20, 0xbfb8aa3b, v61
	v_add_f32_e32 v14, v40, v41
	v_exp_f32_e32 v16, v16
	v_exp_f32_e32 v18, v18
	v_add_f32_dpp v14, v14, v14 quad_perm:[1,0,3,2] row_mask:0xf bank_mask:0xf bound_ctrl:1
	v_exp_f32_e32 v20, v20
	v_add_f32_e32 v16, 1.0, v16
	v_add_f32_dpp v14, v14, v14 quad_perm:[2,3,0,1] row_mask:0xf bank_mask:0xf bound_ctrl:1
	v_add_f32_e32 v18, 1.0, v18
	v_add_f32_e32 v20, 1.0, v20
	v_add_f32_dpp v14, v14, v14 row_half_mirror row_mask:0xf bank_mask:0xf bound_ctrl:1
	v_rcp_f32_e32 v73, v16
	v_rcp_f32_e32 v74, v18
	v_add_f32_dpp v14, v14, v14 row_mirror row_mask:0xf bank_mask:0xf bound_ctrl:1
	v_fmamk_f32 v14, v14, 0x3c800000, v32
	v_rsq_f32_e32 v14, v14
	v_rcp_f32_e32 v75, v20
	v_pk_mul_f32 v[70:71], v[72:73], v[70:71]
	v_lshlrev_b32_e32 v66, 16, v19
	v_pk_mul_f32 v[40:41], v[76:77], v[14:15] op_sel_hi:[1,0]
	v_pk_mul_f32 v[68:69], v[68:69], v[14:15] op_sel_hi:[1,0]
	v_pk_fma_f32 v[40:41], v[2:3], v[40:41], v[6:7]
	v_pk_fma_f32 v[68:69], v[0:1], v[68:69], v[4:5]
	v_pk_mul_f32 v[60:61], v[74:75], v[60:61]
	s_waitcnt vmcnt(6)
; __device__ __forceinline__ f32x4 bf4(v2u u) { return (f32x4){bflo(u.x), bfhi(u.x), bflo(u.y), bfhi(u.y)}; }
; __device__ __forceinline__ v2u pk4(f32x4 v) { v2u o; o.x = pk2(v.x, v.y); o.y = pk2(v.z, v.w); return o; }
; __device__ __forceinline__ void p3_gn_chunk(const Args& a, int ch, int lane) {
;     ...
;     for (int e = 0; e < 4; ++e) { const int t = t0 + e;
;         f32x4 y = bf4(*(const v2u*)(YR + (size_t)t * 1024 + c0));
;         const f32x4 g = bf4(*(const v2u*)(ZB + (size_t)t * 5120 + 4096 + c0)); const float rk = RK[(size_t)t * 16 + head];
;         const float mean = row16_sum((y.x + y.y) + (y.z + y.w)) * (1.f / 64.f);
;         y = y - mean;
;         const float rstd = __builtin_amdgcn_rsqf(row16_sum((y.x * y.x + y.y * y.y) + (y.z * y.z + y.w * y.w)) * (1.f / 64.f) + GN_EPS);
;         const f32x4 v = {vimg[0][e], vimg[1][e], vimg[2][e], vimg[3][e]};
;         f32x4 o = y * rstd * lw + lb + v * rk;
; #pragma unroll
;         for (int k = 0; k < 4; ++k) o[k] *= g[k] * __builtin_amdgcn_rcpf(1.f + __expf(-g[k]));
;         *(v2u*)(Y + (size_t)t * 2048 + c0) = pk4(o); }
	v_pk_fma_f32 v[40:41], v[10:11], v[62:63], v[40:41] op_sel_hi:[0,1,1]
	v_pk_fma_f32 v[54:55], v[10:11], v[54:55], v[68:69] op_sel_hi:[0,1,1]
	v_pk_mul_f32 v[54:55], v[70:71], v[54:55]
	v_pk_mul_f32 v[40:41], v[60:61], v[40:41]
	v_cvt_pk_bf16_f32 v54, v54, v55
	v_cvt_pk_bf16_f32 v55, v40, v41
	global_store_dwordx2 v[26:27], v[54:55], off
	s_waitcnt vmcnt(1)
	v_mov_b32_e32 v26, v100
	v_mov_b32_e32 v27, v101
	v_mov_b32_e32 v28, v102
	v_mov_b32_e32 v29, v103
	v_mov_b32_e32 v10, v104
	s_nop 0
	v_lshlrev_b32_e32 v67, 16, v21
	s_nop 0
	v_lshlrev_b32_e32 v41, 16, v27
	v_lshlrev_b32_e32 v40, 16, v26
	v_and_b32_e32 v27, 0xffff0000, v27
	v_and_b32_e32 v26, 0xffff0000, v26
	v_pk_add_f32 v[44:45], v[40:41], v[26:27]
	s_nop 0
	v_lshlrev_b32_e32 v42, 16, v28
	v_add_f32_e32 v33, v44, v45
	v_mul_f32_e32 v14, 0xbfb8aa3b, v42
	v_exp_f32_e32 v14, v14
	v_add_f32_dpp v33, v33, v33 quad_perm:[1,0,3,2] row_mask:0xf bank_mask:0xf bound_ctrl:1
	v_and_b32_e32 v43, 0xffff0000, v28
	v_lshlrev_b32_e32 v28, 16, v29
	v_add_f32_dpp v33, v33, v33 quad_perm:[2,3,0,1] row_mask:0xf bank_mask:0xf bound_ctrl:1
	v_add_f32_e32 v14, 1.0, v14
	v_rcp_f32_e32 v44, v14
	v_add_f32_dpp v33, v33, v33 row_half_mirror row_mask:0xf bank_mask:0xf bound_ctrl:1
	v_and_b32_e32 v29, 0xffff0000, v29
	v_mul_f32_e32 v16, 0xbfb8aa3b, v43
	v_add_f32_dpp v33, v33, v33 row_mirror row_mask:0xf bank_mask:0xf bound_ctrl:1
	v_fmac_f32_e32 v26, 0xbc800000, v33
	v_fmac_f32_e32 v27, 0xbc800000, v33
	v_fmac_f32_e32 v41, 0xbc800000, v33
	v_fmac_f32_e32 v40, 0xbc800000, v33
	v_mov_b32_e32 v60, v41
	v_mov_b32_e32 v61, v27
	v_mov_b32_e32 v41, v26
	v_pk_mul_f32 v[26:27], v[60:61], v[60:61]
	v_pk_mul_f32 v[62:63], v[40:41], v[40:41]
	v_mul_f32_e32 v18, 0xbfb8aa3b, v28
	v_pk_mov_b32 v[68:69], v[62:63], v[26:27] op_sel:[1,0]
	v_mov_b32_e32 v63, v27
	v_pk_add_f32 v[26:27], v[68:69], v[62:63]
	v_mul_f32_e32 v20, 0xbfb8aa3b, v29
	v_add_f32_e32 v14, v26, v27
	v_exp_f32_e32 v16, v16
	v_exp_f32_e32 v18, v18
	v_add_f32_dpp v14, v14, v14 quad_perm:[1,0,3,2] row_mask:0xf bank_mask:0xf bound_ctrl:1
	v_exp_f32_e32 v20, v20
	v_add_f32_e32 v16, 1.0, v16
	v_add_f32_dpp v14, v14, v14 quad_perm:[2,3,0,1] row_mask:0xf bank_mask:0xf bound_ctrl:1
	v_add_f32_e32 v18, 1.0, v18
	v_add_f32_e32 v20, 1.0, v20
	v_add_f32_dpp v14, v14, v14 row_half_mirror row_mask:0xf bank_mask:0xf bound_ctrl:1
	v_rcp_f32_e32 v45, v16
	v_rcp_f32_e32 v54, v18
	v_add_f32_dpp v14, v14, v14 row_mirror row_mask:0xf bank_mask:0xf bound_ctrl:1
	v_fmamk_f32 v14, v14, 0x3c800000, v32
	v_rsq_f32_e32 v14, v14
	v_rcp_f32_e32 v55, v20
	v_pk_mul_f32 v[42:43], v[44:45], v[42:43]
	v_pk_mul_f32 v[26:27], v[60:61], v[14:15] op_sel_hi:[1,0]
	v_pk_mul_f32 v[40:41], v[40:41], v[14:15] op_sel_hi:[1,0]
	v_pk_fma_f32 v[26:27], v[2:3], v[26:27], v[6:7]
	v_pk_fma_f32 v[40:41], v[0:1], v[40:41], v[4:5]
	v_pk_mul_f32 v[28:29], v[54:55], v[28:29]
	s_nop 0
	v_pk_fma_f32 v[26:27], v[10:11], v[64:65], v[26:27] op_sel_hi:[0,1,1]
	v_pk_fma_f32 v[40:41], v[10:11], v[56:57], v[40:41] op_sel_hi:[0,1,1]
	v_pk_mul_f32 v[40:41], v[42:43], v[40:41]
	v_pk_mul_f32 v[26:27], v[28:29], v[26:27]
	v_cvt_pk_bf16_f32 v28, v40, v41
	v_cvt_pk_bf16_f32 v29, v26, v27
	global_store_dwordx2 v[34:35], v[28:29], off
	s_nop 0
	v_mov_b32_e32 v26, v106
	v_mov_b32_e32 v27, v107
	v_mov_b32_e32 v28, v108
	v_mov_b32_e32 v29, v109
	v_mov_b32_e32 v10, v110
	s_nop 0
	s_nop 0
	v_lshlrev_b32_e32 v35, 16, v27
	v_lshlrev_b32_e32 v34, 16, v26
	v_and_b32_e32 v27, 0xffff0000, v27
	v_and_b32_e32 v26, 0xffff0000, v26
	v_pk_add_f32 v[42:43], v[34:35], v[26:27]
	s_nop 0
	v_lshlrev_b32_e32 v40, 16, v28
	v_add_f32_e32 v33, v42, v43
	v_mul_f32_e32 v14, 0xbfb8aa3b, v40
	v_exp_f32_e32 v14, v14
	v_add_f32_dpp v33, v33, v33 quad_perm:[1,0,3,2] row_mask:0xf bank_mask:0xf bound_ctrl:1
	v_and_b32_e32 v41, 0xffff0000, v28
	v_lshlrev_b32_e32 v28, 16, v29
	v_add_f32_dpp v33, v33, v33 quad_perm:[2,3,0,1] row_mask:0xf bank_mask:0xf bound_ctrl:1
	v_add_f32_e32 v14, 1.0, v14
	v_rcp_f32_e32 v42, v14
	v_add_f32_dpp v33, v33, v33 row_half_mirror row_mask:0xf bank_mask:0xf bound_ctrl:1
	v_and_b32_e32 v29, 0xffff0000, v29
	v_mul_f32_e32 v16, 0xbfb8aa3b, v41
	v_add_f32_dpp v33, v33, v33 row_mirror row_mask:0xf bank_mask:0xf bound_ctrl:1
	v_fmac_f32_e32 v26, 0xbc800000, v33
	v_fmac_f32_e32 v27, 0xbc800000, v33
	v_fmac_f32_e32 v35, 0xbc800000, v33
	v_fmac_f32_e32 v34, 0xbc800000, v33
	v_mov_b32_e32 v46, v35
	v_mov_b32_e32 v47, v27
	v_mov_b32_e32 v35, v26
	v_pk_mul_f32 v[26:27], v[46:47], v[46:47]
	v_pk_mul_f32 v[50:51], v[34:35], v[34:35]
	v_mul_f32_e32 v18, 0xbfb8aa3b, v28
	v_pk_mov_b32 v[52:53], v[50:51], v[26:27] op_sel:[1,0]
; __device__ __forceinline__ f32x4 bf4(v2u u) { return (f32x4){bflo(u.x), bfhi(u.x), bflo(u.y), bfhi(u.y)}; }
; __device__ __forceinline__ v2u pk4(f32x4 v) { v2u o; o.x = pk2(v.x, v.y); o.y = pk2(v.z, v.w); return o; }
; __device__ __forceinline__ void p3_gn_chunk(const Args& a, int ch, int lane) {
;     ...
;     for (int e = 0; e < 4; ++e) { const int t = t0 + e;
;         f32x4 y = bf4(*(const v2u*)(YR + (size_t)t * 1024 + c0));
;         const f32x4 g = bf4(*(const v2u*)(ZB + (size_t)t * 5120 + 4096 + c0)); const float rk = RK[(size_t)t * 16 + head];
;         const float mean = row16_sum((y.x + y.y) + (y.z + y.w)) * (1.f / 64.f);
;         y = y - mean;
;         const float rstd = __builtin_amdgcn_rsqf(row16_sum((y.x * y.x + y.y * y.y) + (y.z * y.z + y.w * y.w)) * (1.f / 64.f) + GN_EPS);
;         const f32x4 v = {vimg[0][e], vimg[1][e], vimg[2][e], vimg[3][e]};
;         f32x4 o = y * rstd * lw + lb + v * rk;
; #pragma unroll
;         for (int k = 0; k < 4; ++k) o[k] *= g[k] * __builtin_amdgcn_rcpf(1.f + __expf(-g[k]));
;         *(v2u*)(Y + (size_t)t * 2048 + c0) = pk4(o); }
	v_mov_b32_e32 v51, v27
	v_pk_add_f32 v[26:27], v[52:53], v[50:51]
	v_mul_f32_e32 v20, 0xbfb8aa3b, v29
	v_add_f32_e32 v14, v26, v27
	v_exp_f32_e32 v16, v16
	v_exp_f32_e32 v18, v18
	v_add_f32_dpp v14, v14, v14 quad_perm:[1,0,3,2] row_mask:0xf bank_mask:0xf bound_ctrl:1
	v_exp_f32_e32 v20, v20
	v_add_f32_e32 v16, 1.0, v16
	v_add_f32_dpp v14, v14, v14 quad_perm:[2,3,0,1] row_mask:0xf bank_mask:0xf bound_ctrl:1
	v_add_f32_e32 v18, 1.0, v18
	v_add_f32_e32 v20, 1.0, v20
	v_add_f32_dpp v14, v14, v14 row_half_mirror row_mask:0xf bank_mask:0xf bound_ctrl:1
	v_rcp_f32_e32 v43, v16
	v_rcp_f32_e32 v44, v18
	v_add_f32_dpp v14, v14, v14 row_mirror row_mask:0xf bank_mask:0xf bound_ctrl:1
	v_fmamk_f32 v14, v14, 0x3c800000, v32
	v_rsq_f32_e32 v14, v14
	v_rcp_f32_e32 v45, v20
	v_pk_mul_f32 v[40:41], v[42:43], v[40:41]
	v_and_b32_e32 v16, 0xffff0000, v19
	v_pk_mul_f32 v[26:27], v[46:47], v[14:15] op_sel_hi:[1,0]
	v_pk_mul_f32 v[34:35], v[34:35], v[14:15] op_sel_hi:[1,0]
	v_pk_fma_f32 v[26:27], v[2:3], v[26:27], v[6:7]
	v_pk_fma_f32 v[34:35], v[0:1], v[34:35], v[4:5]
	v_pk_mul_f32 v[28:29], v[44:45], v[28:29]
	s_nop 0
	v_pk_fma_f32 v[26:27], v[10:11], v[66:67], v[26:27] op_sel_hi:[0,1,1]
	v_pk_fma_f32 v[34:35], v[10:11], v[58:59], v[34:35] op_sel_hi:[0,1,1]
	v_pk_mul_f32 v[34:35], v[40:41], v[34:35]
	v_pk_mul_f32 v[26:27], v[28:29], v[26:27]
	v_cvt_pk_bf16_f32 v28, v34, v35
	v_cvt_pk_bf16_f32 v29, v26, v27
	global_store_dwordx2 v[36:37], v[28:29], off
	s_nop 0
	v_mov_b32_e32 v26, v112
	v_mov_b32_e32 v27, v113
	v_mov_b32_e32 v28, v114
	v_mov_b32_e32 v29, v115
	v_mov_b32_e32 v10, v116
	s_nop 0
	v_lshlrev_b64 v[34:35], 6, v[22:23]
	v_lshl_add_u64 v[34:35], s[4:5], 0, v[34:35]
	v_lshlrev_b64 v[22:23], 12, v[22:23]
	v_and_b32_e32 v14, 0xffff0000, v15
	v_and_b32_e32 v15, 0xffff0000, v17
	v_and_b32_e32 v17, 0xffff0000, v21
	v_lshl_add_u64 v[22:23], v[24:25], 0, v[22:23]
	s_nop 0
	v_lshlrev_b32_e32 v19, 16, v27
	v_lshlrev_b32_e32 v18, 16, v26
	v_and_b32_e32 v21, 0xffff0000, v27
	v_and_b32_e32 v20, 0xffff0000, v26
	s_nop 0
	v_lshlrev_b32_e32 v24, 16, v28
	v_and_b32_e32 v25, 0xffff0000, v28
	v_lshlrev_b32_e32 v26, 16, v29
	v_and_b32_e32 v27, 0xffff0000, v29
	v_pk_add_f32 v[28:29], v[18:19], v[20:21]
	v_mul_f32_e32 v33, 0xbfb8aa3b, v24
	v_add_f32_e32 v28, v28, v29
	v_mul_f32_e32 v34, 0xbfb8aa3b, v25
	v_mul_f32_e32 v35, 0xbfb8aa3b, v26
	v_add_f32_dpp v28, v28, v28 quad_perm:[1,0,3,2] row_mask:0xf bank_mask:0xf bound_ctrl:1
	v_mul_f32_e32 v36, 0xbfb8aa3b, v27
	v_exp_f32_e32 v29, v33
	v_add_f32_dpp v28, v28, v28 quad_perm:[2,3,0,1] row_mask:0xf bank_mask:0xf bound_ctrl:1
	v_exp_f32_e32 v33, v34
	v_exp_f32_e32 v34, v35
	v_add_f32_dpp v28, v28, v28 row_half_mirror row_mask:0xf bank_mask:0xf bound_ctrl:1
	v_exp_f32_e32 v35, v36
	v_add_f32_e32 v29, 1.0, v29
	v_add_f32_dpp v28, v28, v28 row_mirror row_mask:0xf bank_mask:0xf bound_ctrl:1
	v_fmac_f32_e32 v20, 0xbc800000, v28
	v_fmac_f32_e32 v21, 0xbc800000, v28
	v_fmac_f32_e32 v19, 0xbc800000, v28
	v_fmac_f32_e32 v18, 0xbc800000, v28
	v_mov_b32_e32 v36, v19
	v_mov_b32_e32 v37, v21
	v_mov_b32_e32 v19, v20
	v_pk_mul_f32 v[20:21], v[36:37], v[36:37]
	v_pk_mul_f32 v[38:39], v[18:19], v[18:19]
	v_add_f32_e32 v33, 1.0, v33
	v_pk_mov_b32 v[40:41], v[38:39], v[20:21] op_sel:[1,0]
	v_mov_b32_e32 v39, v21
	v_pk_add_f32 v[20:21], v[40:41], v[38:39]
	v_rcp_f32_e32 v28, v29
	v_add_f32_e32 v20, v20, v21
	v_rcp_f32_e32 v29, v33
	v_add_f32_e32 v34, 1.0, v34
	v_add_f32_dpp v20, v20, v20 quad_perm:[1,0,3,2] row_mask:0xf bank_mask:0xf bound_ctrl:1
	v_add_f32_e32 v35, 1.0, v35
	v_rcp_f32_e32 v34, v34
	v_add_f32_dpp v20, v20, v20 quad_perm:[2,3,0,1] row_mask:0xf bank_mask:0xf bound_ctrl:1
	v_rcp_f32_e32 v35, v35
	v_pk_mul_f32 v[24:25], v[28:29], v[24:25]
	v_add_f32_dpp v20, v20, v20 row_half_mirror row_mask:0xf bank_mask:0xf bound_ctrl:1
	v_pk_mul_f32 v[26:27], v[34:35], v[26:27]
	s_nop 0
	v_add_f32_dpp v20, v20, v20 row_mirror row_mask:0xf bank_mask:0xf bound_ctrl:1
	v_fmamk_f32 v20, v20, 0x3c800000, v32
	v_rsq_f32_e32 v20, v20
	s_nop 0
	v_pk_mul_f32 v[28:29], v[36:37], v[20:21] op_sel_hi:[1,0]
	v_pk_mul_f32 v[18:19], v[18:19], v[20:21] op_sel_hi:[1,0]
	v_pk_fma_f32 v[2:3], v[2:3], v[28:29], v[6:7]
	v_pk_fma_f32 v[0:1], v[0:1], v[18:19], v[4:5]
	s_nop 0
	v_pk_fma_f32 v[2:3], v[10:11], v[16:17], v[2:3] op_sel_hi:[0,1,1]
	v_pk_fma_f32 v[0:1], v[10:11], v[14:15], v[0:1] op_sel_hi:[0,1,1]
	v_pk_mul_f32 v[0:1], v[24:25], v[0:1]
	v_pk_mul_f32 v[2:3], v[26:27], v[2:3]
	v_cvt_pk_bf16_f32 v0, v0, v1
	v_cvt_pk_bf16_f32 v1, v2, v3
	global_store_dwordx2 v[22:23], v[0:1], off
	s_cbranch_scc0 .LBB0_640
